# scan compute waves: own loop tail without loader pointer arithmetic and per-chunk constant re-materialisation
# speedup vs baseline: 1.0026x; 1.0012x over previous
.Lcmp_hdr0:
	s_cmp_eq_u32 s33, 1
	s_cbranch_scc1 .Lpf_skip0
	s_cmp_eq_u32 s58, 0
	s_cbranch_scc1 .Lrdy_ok0
	s_waitcnt lgkmcnt(0)
	s_movk_i32 s40, 0x4000

.Lpf_no0:
	v_lshl_add_u64 v[12:13], v[12:13], 0, s[50:51]
	s_add_i32 s58, s58, 1
	s_cmpk_lg_i32 s58, 0x80
	s_cbranch_scc0 .LBB0_506
	s_and_b32 s54, s58, 1
	s_branch .Lcmp_hdr0
